# v27 plus p f32-to-bf16 conversion loop pipelined: 8 loads in flight per thread instead of 1
# speedup vs baseline: 1.0042x; 1.0042x over previous
; DI unsigned pk2(float lo, float hi) { f32x2_t v = {lo, hi}; bf16x2_t b = __builtin_convertvector(v, bf16x2_t); return __builtin_bit_cast(unsigned, b); }
; DI int tid_() { int t = threadIdx.x; asm volatile("" : "+v"(t)); return t; }
; DI int bid_() { return (int)blockIdx.x; }
; __global__ void __launch_bounds__(512) mega(Params p) {
;     ...
;         { const float* ps = p.in[1] + (size_t)L * MTOK * 256;
;             for (size_t i = (size_t)bid_() * 512 + tid_(); i < (size_t)MTOK * 256 / 4; i += (size_t)gridDim.x * 512) { const f32x4 v = *(const f32x4*)(ps + i * 4); u32x2 w; w.x = pk2(v[0], v[1]); w.y = pk2(v[2], v[3]); *(u32x2*)(PB + i * 4) = w; } }
.LBB0_159:
	global_load_dwordx4 v[96:99], v[4:5], off
	v_lshl_add_u64 v[4:5], v[4:5], 0, s[16:17]
	global_load_dwordx4 v[100:103], v[4:5], off
	v_lshl_add_u64 v[4:5], v[4:5], 0, s[16:17]
	global_load_dwordx4 v[104:107], v[4:5], off
	v_lshl_add_u64 v[4:5], v[4:5], 0, s[16:17]
	global_load_dwordx4 v[108:111], v[4:5], off
	v_lshl_add_u64 v[4:5], v[4:5], 0, s[16:17]
	global_load_dwordx4 v[112:115], v[4:5], off
	v_lshl_add_u64 v[4:5], v[4:5], 0, s[16:17]
	global_load_dwordx4 v[116:119], v[4:5], off
	v_lshl_add_u64 v[4:5], v[4:5], 0, s[16:17]
	global_load_dwordx4 v[120:123], v[4:5], off
	v_lshl_add_u64 v[4:5], v[4:5], 0, s[16:17]
	global_load_dwordx4 v[124:127], v[4:5], off
	v_lshl_add_u64 v[4:5], v[4:5], 0, s[16:17]
	s_waitcnt vmcnt(7)
	v_cvt_pk_bf16_f32 v8, v96, v97
	v_cvt_pk_bf16_f32 v9, v98, v99
	global_store_dwordx2 v[6:7], v[8:9], off
	v_lshl_add_u64 v[6:7], v[6:7], 0, s[18:19]
	global_load_dwordx4 v[96:99], v[4:5], off
	v_lshl_add_u64 v[4:5], v[4:5], 0, s[16:17]
	s_waitcnt vmcnt(8)
	v_cvt_pk_bf16_f32 v10, v100, v101
	v_cvt_pk_bf16_f32 v11, v102, v103
	global_store_dwordx2 v[6:7], v[10:11], off
	v_lshl_add_u64 v[6:7], v[6:7], 0, s[18:19]
	global_load_dwordx4 v[100:103], v[4:5], off
	v_lshl_add_u64 v[4:5], v[4:5], 0, s[16:17]
	s_waitcnt vmcnt(9)
	v_cvt_pk_bf16_f32 v8, v104, v105
	v_cvt_pk_bf16_f32 v9, v106, v107
	global_store_dwordx2 v[6:7], v[8:9], off
	v_lshl_add_u64 v[6:7], v[6:7], 0, s[18:19]
	global_load_dwordx4 v[104:107], v[4:5], off
	v_lshl_add_u64 v[4:5], v[4:5], 0, s[16:17]
	s_waitcnt vmcnt(10)
	v_cvt_pk_bf16_f32 v10, v108, v109
	v_cvt_pk_bf16_f32 v11, v110, v111
	global_store_dwordx2 v[6:7], v[10:11], off
	v_lshl_add_u64 v[6:7], v[6:7], 0, s[18:19]
	global_load_dwordx4 v[108:111], v[4:5], off
	v_lshl_add_u64 v[4:5], v[4:5], 0, s[16:17]
	s_waitcnt vmcnt(11)
	v_cvt_pk_bf16_f32 v8, v112, v113
	v_cvt_pk_bf16_f32 v9, v114, v115
	global_store_dwordx2 v[6:7], v[8:9], off
	v_lshl_add_u64 v[6:7], v[6:7], 0, s[18:19]
	global_load_dwordx4 v[112:115], v[4:5], off
	v_lshl_add_u64 v[4:5], v[4:5], 0, s[16:17]
	s_waitcnt vmcnt(12)
	v_cvt_pk_bf16_f32 v10, v116, v117
	v_cvt_pk_bf16_f32 v11, v118, v119
	global_store_dwordx2 v[6:7], v[10:11], off
	v_lshl_add_u64 v[6:7], v[6:7], 0, s[18:19]
	global_load_dwordx4 v[116:119], v[4:5], off
	v_lshl_add_u64 v[4:5], v[4:5], 0, s[16:17]
	s_waitcnt vmcnt(13)
	v_cvt_pk_bf16_f32 v8, v120, v121
	v_cvt_pk_bf16_f32 v9, v122, v123
	global_store_dwordx2 v[6:7], v[8:9], off
	v_lshl_add_u64 v[6:7], v[6:7], 0, s[18:19]
	global_load_dwordx4 v[120:123], v[4:5], off
	v_lshl_add_u64 v[4:5], v[4:5], 0, s[16:17]
	s_waitcnt vmcnt(14)
	v_cvt_pk_bf16_f32 v10, v124, v125
	v_cvt_pk_bf16_f32 v11, v126, v127
	global_store_dwordx2 v[6:7], v[10:11], off
	v_lshl_add_u64 v[6:7], v[6:7], 0, s[18:19]
	global_load_dwordx4 v[124:127], v[4:5], off
	v_lshl_add_u64 v[4:5], v[4:5], 0, s[16:17]
	s_waitcnt vmcnt(14)
	v_cvt_pk_bf16_f32 v8, v96, v97
	v_cvt_pk_bf16_f32 v9, v98, v99
	global_store_dwordx2 v[6:7], v[8:9], off
	v_lshl_add_u64 v[6:7], v[6:7], 0, s[18:19]
	s_waitcnt vmcnt(13)
	v_cvt_pk_bf16_f32 v10, v100, v101
	v_cvt_pk_bf16_f32 v11, v102, v103
	global_store_dwordx2 v[6:7], v[10:11], off
	v_lshl_add_u64 v[6:7], v[6:7], 0, s[18:19]
	s_waitcnt vmcnt(12)
	v_cvt_pk_bf16_f32 v8, v104, v105
	v_cvt_pk_bf16_f32 v9, v106, v107
	global_store_dwordx2 v[6:7], v[8:9], off
	v_lshl_add_u64 v[6:7], v[6:7], 0, s[18:19]
	s_waitcnt vmcnt(11)
	v_cvt_pk_bf16_f32 v10, v108, v109
	v_cvt_pk_bf16_f32 v11, v110, v111
	global_store_dwordx2 v[6:7], v[10:11], off
	v_lshl_add_u64 v[6:7], v[6:7], 0, s[18:19]
	s_waitcnt vmcnt(10)
	v_cvt_pk_bf16_f32 v8, v112, v113
	v_cvt_pk_bf16_f32 v9, v114, v115
	global_store_dwordx2 v[6:7], v[8:9], off
	v_lshl_add_u64 v[6:7], v[6:7], 0, s[18:19]
	s_waitcnt vmcnt(9)
	v_cvt_pk_bf16_f32 v10, v116, v117
	v_cvt_pk_bf16_f32 v11, v118, v119
	global_store_dwordx2 v[6:7], v[10:11], off
	v_lshl_add_u64 v[6:7], v[6:7], 0, s[18:19]
	s_waitcnt vmcnt(8)
	v_cvt_pk_bf16_f32 v8, v120, v121
	v_cvt_pk_bf16_f32 v9, v122, v123
	global_store_dwordx2 v[6:7], v[8:9], off
	v_lshl_add_u64 v[6:7], v[6:7], 0, s[18:19]
	s_waitcnt vmcnt(7)
	v_cvt_pk_bf16_f32 v10, v124, v125
	v_cvt_pk_bf16_f32 v11, v126, v127
	global_store_dwordx2 v[6:7], v[10:11], off
	v_lshl_add_u64 v[6:7], v[6:7], 0, s[18:19]
